# P0: weight-transpose items rebalanced so the 64 workgroups that also run ssm_gen take 4 items per wave and the other 192 take 25 (deferred SSQ atomics kept)
# speedup vs baseline: 1.0010x; 1.0010x over previous
; __global__ void __launch_bounds__(NTHR, 2) mk_fwd(Args args) {
;     ...
;         if (gw < NTR) { TrItem cur, nxt; f32x4 ra[8], rb[8]; int it = gw; P0_DECODE(it, cur); tr_load(cur, lane, ra);
;             for (;;) { const int itn = it + NGW; const bool has = itn < NTR;
;                 if (has) { P0_DECODE(itn, nxt); tr_load(nxt, lane, rb); }
.LBB0_112:
	s_mov_b32 s81, s72
	s_mov_b32 s82, s80
	s_mov_b32 s83, 0x9e00
	s_cmpk_lg_i32 s70, 0x100
	s_cbranch_scc1 .Lp0_rb_done
	s_add_i32 s81, s72, 0xfffffe00
	s_movk_i32 s82, 0x600
	s_mov_b32 s83, 38400
	s_cmp_gt_i32 s2, 63
	s_cbranch_scc1 .Lp0_rb_done
	s_add_i32 s81, s72, 38400
	s_movk_i32 s82, 0x200
	s_mov_b32 s83, 0x9e00

; #define LAS __attribute__((address_space(3)))
; #define LDS_WAIT() asm volatile("s_waitcnt lgkmcnt(0)" ::: "memory")
; __device__ __forceinline__ unsigned pk2(float lo, float hi) { return f2bf(lo) | (f2bf(hi) << 16); }
; __device__ __forceinline__ void tr_load(const TrItem& t, int lane, f32x4 (&r)[8]) {
;     const int nblk = t.N / 32, kb = t.item / nblk, nb = t.item % nblk;
;     const float* p = t.W + (size_t)(64 * kb + (lane >> 3)) * t.N + 32 * nb + (lane & 7) * 4;
; #pragma unroll
;     for (int i = 0; i < 8; ++i) r[i] = *(const f32x4*)(p + (size_t)(8 * i) * t.N);
; }
; __device__ __forceinline__ void tr_store(const TrItem& t, int lane, const f32x4 (&r)[8], LAS float* scr) {
;     const int nblk = t.N / 32, kb = t.item / nblk, nb = t.item % nblk, k0 = 64 * kb, n0 = 32 * nb;
; #pragma unroll
;     for (int i = 0; i < 8; ++i) { LAS float* d = scr + (8 * i + (lane >> 3)) * 33 + (lane & 7) * 4; d[0] = r[i].x; d[1] = r[i].y; d[2] = r[i].z; d[3] = r[i].w; }
;     LDS_WAIT(); asm volatile("" ::: "memory");
;     const int c = lane & 7;
; #pragma unroll
;     for (int j = 0; j < 4; ++j) { const int n = (lane >> 3) + 8 * j; const LAS float* s = scr + (8 * c) * 33 + n;
;         v4u o; o.x = pk2(s[0 * 33], s[1 * 33]); o.y = pk2(s[2 * 33], s[3 * 33]); o.z = pk2(s[4 * 33], s[5 * 33]); o.w = pk2(s[6 * 33], s[7 * 33]);
;         const int nn = n0 + n; int drow = t.mode == 0 ? nn : ((nn >> 7) * 256 + (t.mode == 2 ? 128 : 0) + (nn & 127));
;         if (t.mode == 3) drow = nn < 2048 ? ((nn >> 8) * 256 + ((nn >> 5) & 1) * 128 + ((nn >> 6) & 3) * 32 + (nn & 31)) : nn;
;         *(v4u*)(t.WT + (size_t)drow * t.K + k0 + 8 * c) = o; }
; __global__ void __launch_bounds__(NTHR, 2) mk_fwd(Args args) {
;     ...
;         if (gw < NTR) { TrItem cur, nxt; f32x4 ra[8], rb[8]; int it = gw; P0_DECODE(it, cur); tr_load(cur, lane, ra);
;             for (;;) { const int itn = it + NGW; const bool has = itn < NTR;
.LBB0_152:
	s_lshl_b32 s8, s93, 14
	s_add_i32 s11, s8, 0
	s_add_u32 s8, s7, s4
	s_addc_u32 s9, s10, s5
	s_lshr_b32 s4, s6, 5
	s_waitcnt lgkmcnt(0)
	v_cvt_f32_u32_e32 v0, s4
	s_sub_i32 s12, 0, s4
	s_abs_i32 s10, s3
	s_ashr_i32 s5, s3, 31
	v_rcp_iflag_f32_e32 v0, v0
	v_ashrrev_i32_e32 v76, 3, v88
	s_mov_b32 s7, 0
	v_mov_b32_e32 v65, 0
	v_mul_f32_e32 v0, 0x4f7ffffe, v0
	v_cvt_u32_f32_e32 v0, v0
	v_add_u32_e32 v77, 8, v76
	v_add_u32_e32 v78, 16, v76
	v_add_u32_e32 v79, 24, v76
	v_readfirstlane_b32 s13, v0
	s_mul_i32 s12, s12, s13
	s_mul_hi_u32 s12, s13, s12
	s_add_i32 s13, s13, s12
	s_mul_hi_u32 s12, s10, s13
	s_mul_i32 s13, s12, s4
	s_sub_i32 s10, s10, s13
	s_add_i32 s14, s12, 1
	s_sub_i32 s13, s10, s4
	s_cmp_ge_u32 s10, s4
	s_cselect_b32 s12, s14, s12
	s_cselect_b32 s10, s13, s10
	s_add_i32 s13, s12, 1
	s_cmp_ge_u32 s10, s4
	s_cselect_b32 s10, s13, s12
	s_xor_b32 s10, s10, s5
	s_sub_i32 s5, s10, s5
	s_mul_i32 s4, s5, s4
	v_lshl_add_u32 v0, s5, 6, v76
	s_sub_i32 s10, s3, s4
	v_ashrrev_i32_e32 v3, 31, v0
	v_mad_u64_u32 v[0:1], s[4:5], v0, s6, 0
	v_mov_b32_e32 v2, v1
	v_mad_u64_u32 v[2:3], s[4:5], v3, s6, v[2:3]
	v_mov_b32_e32 v1, v2
	v_lshl_add_u64 v[0:1], v[0:1], 2, s[0:1]
	s_lshl_b32 s0, s10, 5
	v_lshlrev_b32_e32 v2, 2, v88
	s_ashr_i32 s1, s0, 31
	v_and_b32_e32 v32, 28, v2
	v_lshl_add_u64 v[0:1], s[0:1], 2, v[0:1]
	v_lshlrev_b32_e32 v64, 2, v32
	v_lshl_add_u64 v[8:9], v[0:1], 0, v[64:65]
	s_lshl_b64 s[0:1], s[6:7], 5
	v_lshl_add_u64 v[10:11], v[8:9], 0, s[0:1]
	v_lshl_add_u64 v[16:17], v[10:11], 0, s[0:1]
	v_lshl_add_u64 v[18:19], v[16:17], 0, s[0:1]
	v_lshl_add_u64 v[24:25], v[18:19], 0, s[0:1]
	v_lshl_add_u64 v[26:27], v[24:25], 0, s[0:1]
	v_lshl_add_u64 v[34:35], v[26:27], 0, s[0:1]
	global_load_dwordx4 v[0:3], v[8:9], off
	global_load_dwordx4 v[4:7], v[10:11], off
	s_nop 0
	global_load_dwordx4 v[8:11], v[16:17], off
	global_load_dwordx4 v[12:15], v[18:19], off
	s_nop 0
	global_load_dwordx4 v[16:19], v[24:25], off
	global_load_dwordx4 v[20:23], v[26:27], off
	v_lshl_add_u64 v[36:37], v[34:35], 0, s[0:1]
	global_load_dwordx4 v[24:27], v[34:35], off
	global_load_dwordx4 v[28:31], v[36:37], off
	v_lshlrev_b32_e32 v34, 3, v88
	s_movk_i32 s0, 0x84
	v_and_b32_e32 v34, 56, v34
	v_add_u32_e32 v33, s11, v64
	v_mul_lo_u32 v35, v76, s0
	v_mul_u32_u24_e32 v36, 0x84, v34
	v_lshlrev_b32_e32 v37, 2, v76
	v_add3_u32 v80, s11, v36, v37
	v_and_b32_e32 v81, 31, v76
	v_and_b32_e32 v82, 31, v77
	v_and_b32_e32 v83, 31, v78
	v_and_b32_e32 v84, 31, v79
	s_add_i32 s22, 0, 0x20118
	s_add_i32 s23, 0, 0x20108
	s_add_i32 s24, 0, 0x20100
	s_add_i32 s25, 0, 0x200f8
	s_add_i32 s26, 0, 0x200e8
	s_add_i32 s27, 0, 0x200d0
	s_add_i32 s28, 0, 0x20050
	s_add_i32 s29, 0, 0x20040
	s_add_i32 s30, 0, 0x20038
	s_add_i32 s31, 0, 0x20030
	v_lshlrev_b32_e32 v66, 2, v32
	v_add_u32_e32 v85, v33, v35
	s_movk_i32 s36, 0xff00
	s_movk_i32 s37, 0x800
	s_movk_i32 s38, 0x7fff
	s_mov_b32 s39, 0xffff0000
	v_lshlrev_b32_e32 v64, 1, v34
	s_mov_b32 s40, s6
	s_mov_b32 s41, s81
	s_branch .LBB0_154
